# v28 + L1 window bias gather: per-element address VALU (add/med3/lshl_add x32) replaced by one base + ds_read_b32 immediate offsets
# speedup vs baseline: 1.0045x; 1.0045x over previous
.LBB0_422:
	s_mul_i32 s19, s20, 0x4c00
	v_add_u32_e32 v0, s19, v157
	ds_read_b128 v[206:209], v0
	ds_read_b128 v[210:213], v0 offset:4608
	ds_read_b128 v[214:217], v0 offset:32
	s_waitcnt lgkmcnt(2)
	v_mfma_f32_32x32x16_bf16 v[50:65], v[206:209], v[66:69], v[220:235]
	v_add_f32_e64 v90, v116, 0
	v_add_f32_e64 v91, v117, 0
	v_cvt_pk_bf16_f32 v102, v116, v117
	v_add_f32_e64 v90, v118, v90
	v_add_f32_e64 v91, v119, v91
	v_cvt_pk_bf16_f32 v103, v118, v119
	s_waitcnt lgkmcnt(1)
	v_mfma_f32_32x32x16_bf16 v[34:49], v[210:213], v[66:69], v[220:235]
	ds_read_b128 v[116:119], v0 offset:4640
	v_add_f32_e64 v90, v104, v90
	v_add_f32_e64 v91, v105, v91
	v_cvt_pk_bf16_f32 v104, v104, v105
	v_add_f32_e64 v90, v120, v90
	v_add_f32_e64 v91, v121, v91
	v_cvt_pk_bf16_f32 v105, v120, v121
	s_waitcnt lgkmcnt(1)
	v_mfma_f32_32x32x16_bf16 v[50:65], v[214:217], v[70:73], v[50:65]
	ds_read_b128 v[206:209], v0 offset:64
	v_add_f32_e64 v90, v122, v90
	v_add_f32_e64 v91, v123, v91
	v_cvt_pk_bf16_f32 v98, v122, v123
	v_add_f32_e64 v90, v126, v90
	v_add_f32_e64 v91, v127, v91
	v_cvt_pk_bf16_f32 v99, v126, v127
	s_waitcnt lgkmcnt(1)
	v_mfma_f32_32x32x16_bf16 v[34:49], v[116:119], v[70:73], v[34:49]
	ds_read_b128 v[120:123], v0 offset:4672
	v_add_f32_e64 v90, v100, v90
	v_add_f32_e64 v91, v101, v91
	v_cvt_pk_bf16_f32 v100, v100, v101
	v_add_f32_e64 v90, v130, v90
	v_add_f32_e64 v91, v131, v91
	v_cvt_pk_bf16_f32 v101, v130, v131
	s_waitcnt lgkmcnt(1)
	v_mfma_f32_32x32x16_bf16 v[50:65], v[206:209], v[74:77], v[50:65]
	ds_read_b128 v[116:119], v0 offset:96
	v_add_f32_e64 v90, v124, v90
	v_add_f32_e64 v91, v125, v91
	v_cvt_pk_bf16_f32 v94, v124, v125
	v_add_f32_e64 v90, v128, v90
	v_add_f32_e64 v91, v129, v91
	v_cvt_pk_bf16_f32 v95, v128, v129
	s_waitcnt lgkmcnt(1)
	v_mfma_f32_32x32x16_bf16 v[34:49], v[120:123], v[74:77], v[34:49]
	ds_read_b128 v[124:127], v0 offset:4704
	v_add_f32_e64 v90, v96, v90
	v_add_f32_e64 v91, v97, v91
	v_cvt_pk_bf16_f32 v96, v96, v97
	v_add_f32_e64 v90, v132, v90
	v_add_f32_e64 v91, v133, v91
	v_cvt_pk_bf16_f32 v97, v132, v133
	s_waitcnt lgkmcnt(1)
	v_mfma_f32_32x32x16_bf16 v[50:65], v[116:119], v[78:81], v[50:65]
	v_add_f32_e64 v116, v134, v90
	v_add_f32_e64 v117, v135, v91
	v_cvt_pk_bf16_f32 v90, v134, v135
	v_add_f32_e64 v116, v136, v116
	v_add_f32_e64 v117, v137, v117
	v_cvt_pk_bf16_f32 v91, v136, v137
	s_waitcnt lgkmcnt(0)
	v_mfma_f32_32x32x16_bf16 v[34:49], v[124:127], v[78:81], v[34:49]
	v_add_f32_e64 v116, v92, v116
	v_add_f32_e64 v117, v93, v117
	v_cvt_pk_bf16_f32 v92, v92, v93
	v_add_f32_e64 v116, v138, v116
	v_add_f32_e64 v117, v139, v117
	v_cvt_pk_bf16_f32 v93, v138, v139
	s_cmp_lt_u32 s7, 8
	s_cbranch_scc1 .LBB0_424
	s_add_i32 s6, s16, s17
	s_addk_i32 s6, 0xfe40
	s_ashr_i32 s22, s6, 6
	v_sub_u32_e32 v0, s22, v159
	v_mul_lo_u32 v0, v0, 31
	v_sub_u32_e32 v0, v0, v150
	v_add_u32_e32 v0, 0xe8, v0
	v_add_u32_e32 v239, v0, v161
	v_lshl_add_u32 v239, v239, 2, v203
	ds_read_b32 v118, v239
	ds_read_b32 v218, v239 offset:4
	ds_read_b32 v219, v239 offset:8
	ds_read_b32 v236, v239 offset:12
	ds_read_b32 v237, v239 offset:16
	ds_read_b32 v238, v239 offset:20
	v_cmp_ge_i32_e64 s[6:7], s22, v160
	v_cmp_lt_i32_e32 vcc, s22, v162
	s_and_b64 s[6:7], s[6:7], vcc
	s_and_b64 vcc, s[6:7], s[36:37]
	s_waitcnt lgkmcnt(5)
	v_add_f32_e32 v50, v50, v118
	v_cndmask_b32_e32 v50, v201, v50, vcc
	ds_read_b32 v118, v239 offset:24
	s_and_b64 vcc, s[6:7], s[38:39]
	s_waitcnt lgkmcnt(5)
	v_add_f32_e32 v51, v51, v218
	v_cndmask_b32_e32 v51, v201, v51, vcc
	ds_read_b32 v218, v239 offset:28
	s_and_b64 vcc, s[6:7], s[40:41]
	s_waitcnt lgkmcnt(5)
	v_add_f32_e32 v52, v52, v219
	v_cndmask_b32_e32 v52, v201, v52, vcc
	ds_read_b32 v219, v239 offset:64
	s_and_b64 vcc, s[6:7], s[42:43]
	s_waitcnt lgkmcnt(5)
	v_add_f32_e32 v53, v53, v236
	v_cndmask_b32_e32 v53, v201, v53, vcc
	ds_read_b32 v236, v239 offset:68
	s_and_b64 vcc, s[6:7], s[44:45]
	s_waitcnt lgkmcnt(5)
	v_add_f32_e32 v54, v54, v237
	v_cndmask_b32_e32 v54, v201, v54, vcc
	ds_read_b32 v237, v239 offset:72
	s_and_b64 vcc, s[6:7], s[46:47]
	s_waitcnt lgkmcnt(5)
	v_add_f32_e32 v55, v55, v238
	v_cndmask_b32_e32 v55, v201, v55, vcc
	ds_read_b32 v238, v239 offset:76
	s_and_b64 vcc, s[6:7], s[10:11]
	s_waitcnt lgkmcnt(5)
	v_add_f32_e32 v56, v56, v118
	v_cndmask_b32_e32 v56, v201, v56, vcc
	ds_read_b32 v118, v239 offset:80
	s_and_b64 vcc, s[6:7], s[50:51]
	s_waitcnt lgkmcnt(5)
	v_add_f32_e32 v57, v57, v218
	v_cndmask_b32_e32 v57, v201, v57, vcc
	ds_read_b32 v218, v239 offset:84
	s_and_b64 vcc, s[6:7], s[52:53]
	s_waitcnt lgkmcnt(5)
	v_add_f32_e32 v58, v58, v219
	v_cndmask_b32_e32 v58, v201, v58, vcc
	ds_read_b32 v219, v239 offset:88
	s_and_b64 vcc, s[6:7], s[54:55]
	s_waitcnt lgkmcnt(5)
	v_add_f32_e32 v59, v59, v236
	v_cndmask_b32_e32 v59, v201, v59, vcc
	ds_read_b32 v236, v239 offset:92
	s_and_b64 vcc, s[6:7], s[56:57]
	s_waitcnt lgkmcnt(5)
	v_add_f32_e32 v60, v60, v237
	v_cndmask_b32_e32 v60, v201, v60, vcc
	ds_read_b32 v237, v239 offset:128
	s_and_b64 vcc, s[6:7], s[58:59]
	s_waitcnt lgkmcnt(5)
	v_add_f32_e32 v61, v61, v238
	v_cndmask_b32_e32 v61, v201, v61, vcc
	ds_read_b32 v238, v239 offset:132
	s_and_b64 vcc, s[6:7], s[60:61]
	s_waitcnt lgkmcnt(5)
	v_add_f32_e32 v62, v62, v118
	v_cndmask_b32_e32 v62, v201, v62, vcc
	ds_read_b32 v118, v239 offset:136
	s_and_b64 vcc, s[6:7], s[62:63]
	s_waitcnt lgkmcnt(5)
	v_add_f32_e32 v63, v63, v218
	v_cndmask_b32_e32 v63, v201, v63, vcc
	ds_read_b32 v218, v239 offset:140
	s_and_b64 vcc, s[6:7], s[64:65]
	s_waitcnt lgkmcnt(5)
	v_add_f32_e32 v64, v64, v219
	v_cndmask_b32_e32 v64, v201, v64, vcc
	ds_read_b32 v219, v239 offset:144
	s_and_b64 vcc, s[6:7], s[66:67]
	s_waitcnt lgkmcnt(5)
	v_add_f32_e32 v65, v65, v236
	v_cndmask_b32_e32 v65, v201, v65, vcc
	ds_read_b32 v236, v239 offset:148
	s_and_b64 vcc, s[6:7], s[68:69]
	s_waitcnt lgkmcnt(5)
	v_add_f32_e32 v34, v34, v237
	v_cndmask_b32_e32 v34, v201, v34, vcc
	ds_read_b32 v237, v239 offset:152
	s_and_b64 vcc, s[6:7], s[70:71]
	s_waitcnt lgkmcnt(5)
	v_add_f32_e32 v35, v35, v238
	v_cndmask_b32_e32 v35, v201, v35, vcc
	ds_read_b32 v238, v239 offset:156
	s_and_b64 vcc, s[6:7], s[72:73]
	s_waitcnt lgkmcnt(5)
	v_add_f32_e32 v36, v36, v118
	v_cndmask_b32_e32 v36, v201, v36, vcc
	ds_read_b32 v118, v239 offset:192
	s_and_b64 vcc, s[6:7], s[74:75]
	s_waitcnt lgkmcnt(5)
	v_add_f32_e32 v37, v37, v218
	v_cndmask_b32_e32 v37, v201, v37, vcc
	ds_read_b32 v218, v239 offset:196
	s_and_b64 vcc, s[6:7], s[76:77]
	s_waitcnt lgkmcnt(5)
	v_add_f32_e32 v38, v38, v219
	v_cndmask_b32_e32 v38, v201, v38, vcc
	ds_read_b32 v219, v239 offset:200
	s_and_b64 vcc, s[6:7], s[78:79]
	s_waitcnt lgkmcnt(5)
	v_add_f32_e32 v39, v39, v236
	v_cndmask_b32_e32 v39, v201, v39, vcc
	ds_read_b32 v236, v239 offset:204
	s_and_b64 vcc, s[6:7], s[0:1]
	s_waitcnt lgkmcnt(5)
	v_add_f32_e32 v40, v40, v237
	v_cndmask_b32_e32 v40, v201, v40, vcc
	ds_read_b32 v237, v239 offset:208
	s_and_b64 vcc, s[6:7], s[82:83]
	s_waitcnt lgkmcnt(5)
	v_add_f32_e32 v41, v41, v238
	v_cndmask_b32_e32 v41, v201, v41, vcc
	ds_read_b32 v238, v239 offset:212
	s_and_b64 vcc, s[6:7], s[84:85]
	s_waitcnt lgkmcnt(5)
	v_add_f32_e32 v42, v42, v118
	v_cndmask_b32_e32 v42, v201, v42, vcc
	ds_read_b32 v118, v239 offset:216
	s_and_b64 vcc, s[6:7], s[86:87]
	s_waitcnt lgkmcnt(5)
	v_add_f32_e32 v43, v43, v218
	v_cndmask_b32_e32 v43, v201, v43, vcc
	ds_read_b32 v218, v239 offset:220
	s_and_b64 vcc, s[6:7], s[88:89]
	s_waitcnt lgkmcnt(5)
	v_add_f32_e32 v44, v44, v219
	v_cndmask_b32_e32 v44, v201, v44, vcc
	s_and_b64 vcc, s[6:7], s[90:91]
	s_waitcnt lgkmcnt(4)
	v_add_f32_e32 v45, v45, v236
	v_cndmask_b32_e32 v45, v201, v45, vcc
	s_and_b64 vcc, s[6:7], s[92:93]
	s_waitcnt lgkmcnt(3)
	v_add_f32_e32 v46, v46, v237
	v_cndmask_b32_e32 v46, v201, v46, vcc
	s_and_b64 vcc, s[6:7], s[94:95]
	s_waitcnt lgkmcnt(2)
	v_add_f32_e32 v47, v47, v238
	v_cndmask_b32_e32 v47, v201, v47, vcc
	s_and_b64 vcc, s[6:7], s[96:97]
	s_waitcnt lgkmcnt(1)
	v_add_f32_e32 v48, v48, v118
	v_cndmask_b32_e32 v48, v201, v48, vcc
	s_and_b64 vcc, s[6:7], s[4:5]
	s_waitcnt lgkmcnt(0)
	v_add_f32_e32 v49, v49, v218
	v_cndmask_b32_e32 v49, v201, v49, vcc
